# sparse attention leading waves: row max of the first accumulator taken in the gaps of the second accumulator's MFMA chain; remaining max3 behind a full MFMA-to-VALU distance
# baseline (speedup 1.0000x reference)
.LBB0_67:
	s_mul_i32 s0, s49, 0x8c00
	s_add_i32 s47, s0, 0
	v_add3_u32 v217, s47, v209, v210
	v_lshrrev_b32_e32 v218, v186, v202
	v_lshrrev_b32_e32 v203, v186, v203
	s_and_saveexec_b64 s[0:1], s[6:7]
	s_xor_b64 s[0:1], exec, s[0:1]
	s_cbranch_execz .LBB0_71
	v_bfe_i32 v66, v218, 0, 1
	v_bfe_i32 v67, v218, 1, 1
	v_bfe_i32 v68, v218, 2, 1
	v_bfe_i32 v69, v218, 3, 1
	v_bfe_i32 v70, v218, 8, 1
	v_bfe_i32 v71, v218, 9, 1
	v_bfe_i32 v72, v218, 10, 1
	v_bfe_i32 v73, v218, 11, 1
	v_bfe_i32 v74, v218, 16, 1
	v_bfe_i32 v75, v218, 17, 1
	v_bfe_i32 v76, v218, 18, 1
	v_bfe_i32 v77, v218, 19, 1
	v_bfe_i32 v78, v218, 24, 1
	v_bfe_i32 v79, v218, 25, 1
	v_bfe_i32 v80, v218, 26, 1
	v_bfe_i32 v81, v218, 27, 1
	ds_read_b128 v[218:221], v217
	ds_read_b128 v[222:225], v217 offset:32
	ds_read_b128 v[226:229], v217 offset:64
	ds_read_b128 v[232:235], v217 offset:96
	ds_read_b128 v[236:239], v217 offset:128
	ds_read_b128 v[248:251], v217 offset:160
	ds_read_b128 v[240:243], v217 offset:192
	ds_read_b128 v[174:177], v217 offset:224
	v_bfi_b32 v66, v66, v230, v231
	v_bfi_b32 v67, v67, v230, v231
	v_bfi_b32 v68, v68, v230, v231
	v_bfi_b32 v69, v69, v230, v231
	v_bfi_b32 v70, v70, v230, v231
	v_bfi_b32 v71, v71, v230, v231
	v_bfi_b32 v72, v72, v230, v231
	v_bfi_b32 v73, v73, v230, v231
	v_bfi_b32 v74, v74, v230, v231
	v_bfi_b32 v75, v75, v230, v231
	v_bfi_b32 v76, v76, v230, v231
	v_bfi_b32 v77, v77, v230, v231
	v_bfi_b32 v78, v78, v230, v231
	v_bfi_b32 v79, v79, v230, v231
	v_bfi_b32 v80, v80, v230, v231
	v_bfi_b32 v81, v81, v230, v231
	s_setprio 1
	s_waitcnt lgkmcnt(7)
	v_mfma_f32_32x32x16_bf16 v[66:81], v[218:221], v[98:101], v[66:81]
	ds_read_b128 v[218:221], v217 offset:8704
	v_bfe_i32 v82, v203, 0, 1
	v_bfe_i32 v83, v203, 1, 1
	v_bfe_i32 v84, v203, 2, 1
	v_bfe_i32 v85, v203, 3, 1
	v_bfe_i32 v86, v203, 8, 1
	s_waitcnt lgkmcnt(7)
	v_mfma_f32_32x32x16_bf16 v[66:81], v[222:225], v[102:105], v[66:81]
	ds_read_b128 v[222:225], v217 offset:8736
	v_bfe_i32 v87, v203, 9, 1
	v_bfe_i32 v88, v203, 10, 1
	v_bfe_i32 v89, v203, 11, 1
	v_bfe_i32 v90, v203, 16, 1
	v_bfe_i32 v91, v203, 17, 1
	s_waitcnt lgkmcnt(7)
	v_mfma_f32_32x32x16_bf16 v[66:81], v[226:229], v[106:109], v[66:81]
	ds_read_b128 v[226:229], v217 offset:8768
	v_bfe_i32 v92, v203, 18, 1
	v_bfe_i32 v93, v203, 19, 1
	v_bfe_i32 v94, v203, 24, 1
	v_bfe_i32 v95, v203, 25, 1
	v_bfe_i32 v96, v203, 26, 1
	s_waitcnt lgkmcnt(7)
	v_mfma_f32_32x32x16_bf16 v[66:81], v[232:235], v[110:113], v[66:81]
	ds_read_b128 v[232:235], v217 offset:8800
	v_bfe_i32 v97, v203, 27, 1
	v_bfi_b32 v82, v82, v230, v231
	v_bfi_b32 v83, v83, v230, v231
	v_bfi_b32 v84, v84, v230, v231
	v_bfi_b32 v85, v85, v230, v231
	s_waitcnt lgkmcnt(7)
	v_mfma_f32_32x32x16_bf16 v[66:81], v[236:239], v[114:117], v[66:81]
	ds_read_b128 v[236:239], v217 offset:8832
	v_bfi_b32 v86, v86, v230, v231
	v_bfi_b32 v87, v87, v230, v231
	v_bfi_b32 v88, v88, v230, v231
	v_bfi_b32 v89, v89, v230, v231
	s_waitcnt lgkmcnt(7)
	v_mfma_f32_32x32x16_bf16 v[66:81], v[248:251], v[118:121], v[66:81]
	ds_read_b128 v[248:251], v217 offset:8864
	v_bfi_b32 v90, v90, v230, v231
	v_bfi_b32 v91, v91, v230, v231
	v_bfi_b32 v92, v92, v230, v231
	v_bfi_b32 v93, v93, v230, v231
	s_waitcnt lgkmcnt(7)
	v_mfma_f32_32x32x16_bf16 v[66:81], v[240:243], v[122:125], v[66:81]
	ds_read_b128 v[240:243], v217 offset:8896
	v_bfi_b32 v94, v94, v230, v231
	v_bfi_b32 v95, v95, v230, v231
	v_bfi_b32 v96, v96, v230, v231
	v_bfi_b32 v97, v97, v230, v231
	s_waitcnt lgkmcnt(7)
	v_mfma_f32_32x32x16_bf16 v[66:81], v[174:177], v[126:129], v[66:81]
	ds_read_b128 v[174:177], v217 offset:8928
	s_waitcnt lgkmcnt(7)
	v_mfma_f32_32x32x16_bf16 v[82:97], v[218:221], v[98:101], v[82:97]
	s_waitcnt lgkmcnt(6)
	v_mfma_f32_32x32x16_bf16 v[82:97], v[222:225], v[102:105], v[82:97]
	s_waitcnt lgkmcnt(5)
	v_mfma_f32_32x32x16_bf16 v[82:97], v[226:229], v[106:109], v[82:97]
	v_max3_f32 v195, v231, v66, v67
	v_max3_f32 v195, v195, v68, v69
	s_waitcnt lgkmcnt(4)
	v_mfma_f32_32x32x16_bf16 v[82:97], v[232:235], v[110:113], v[82:97]
	v_max3_f32 v195, v195, v70, v71
	v_max3_f32 v195, v195, v72, v73
	s_waitcnt lgkmcnt(3)
	v_mfma_f32_32x32x16_bf16 v[82:97], v[236:239], v[114:117], v[82:97]
	v_max3_f32 v195, v195, v74, v75
	v_max3_f32 v195, v195, v76, v77
	s_waitcnt lgkmcnt(2)
	v_mfma_f32_32x32x16_bf16 v[82:97], v[248:251], v[118:121], v[82:97]
	v_max3_f32 v195, v195, v78, v79
	v_max3_f32 v195, v195, v80, v81
	s_waitcnt lgkmcnt(1)
	v_mfma_f32_32x32x16_bf16 v[82:97], v[240:243], v[122:125], v[82:97]
	s_waitcnt lgkmcnt(0)
	v_mfma_f32_32x32x16_bf16 v[82:97], v[174:177], v[126:129], v[82:97]
	s_setprio 0
	s_nop 10
	v_max3_f32 v174, v195, v82, v83
	v_max3_f32 v174, v174, v84, v85
	v_max3_f32 v174, v174, v86, v87
	v_max3_f32 v174, v174, v88, v89
	v_max3_f32 v174, v174, v90, v91
	v_max3_f32 v174, v174, v92, v93
	v_max3_f32 v174, v174, v94, v95
	v_max3_f32 v174, v174, v96, v97
	v_mov_b32_e32 v175, v174
	s_nop 1
	v_permlane32_swap_b32_e32 v174, v175
	v_max_f32_e32 v174, v174, v175
	v_cmp_gt_f32_e32 vcc, v174, v245
	s_cmp_eq_u64 vcc, 0
	s_cbranch_scc1 .Lsmf_0
	v_cndmask_b32_e32 v203, 0, v174, vcc
	v_mov_b32_e32 v175, 0x41000000
	v_cndmask_b32_e32 v245, v245, v175, vcc
	v_sub_f32_e32 v230, v230, v203
	v_max_f32_e32 v175, 0, v203
	v_exp_f32_e64 v202, -v175
	s_nop 0
	v_pk_mul_f32 v[64:65], v[64:65], v[202:203] op_sel_hi:[1,0]
	v_pk_mul_f32 v[62:63], v[62:63], v[202:203] op_sel_hi:[1,0]
	v_pk_mul_f32 v[60:61], v[60:61], v[202:203] op_sel_hi:[1,0]
	v_pk_mul_f32 v[58:59], v[58:59], v[202:203] op_sel_hi:[1,0]
	v_pk_mul_f32 v[56:57], v[56:57], v[202:203] op_sel_hi:[1,0]
	v_pk_mul_f32 v[54:55], v[54:55], v[202:203] op_sel_hi:[1,0]
	v_pk_mul_f32 v[52:53], v[52:53], v[202:203] op_sel_hi:[1,0]
	v_pk_mul_f32 v[50:51], v[50:51], v[202:203] op_sel_hi:[1,0]
	v_pk_mul_f32 v[48:49], v[48:49], v[202:203] op_sel_hi:[1,0]
	v_pk_mul_f32 v[46:47], v[46:47], v[202:203] op_sel_hi:[1,0]
	v_pk_mul_f32 v[44:45], v[44:45], v[202:203] op_sel_hi:[1,0]
	v_pk_mul_f32 v[42:43], v[42:43], v[202:203] op_sel_hi:[1,0]
	v_pk_mul_f32 v[40:41], v[40:41], v[202:203] op_sel_hi:[1,0]
	v_pk_mul_f32 v[38:39], v[38:39], v[202:203] op_sel_hi:[1,0]
	v_pk_mul_f32 v[36:37], v[36:37], v[202:203] op_sel_hi:[1,0]
	v_pk_mul_f32 v[34:35], v[34:35], v[202:203] op_sel_hi:[1,0]
	v_pk_mul_f32 v[32:33], v[32:33], v[202:203] op_sel_hi:[1,0]
	v_pk_mul_f32 v[30:31], v[30:31], v[202:203] op_sel_hi:[1,0]
	v_pk_mul_f32 v[28:29], v[28:29], v[202:203] op_sel_hi:[1,0]
	v_pk_mul_f32 v[26:27], v[26:27], v[202:203] op_sel_hi:[1,0]
	v_pk_mul_f32 v[24:25], v[24:25], v[202:203] op_sel_hi:[1,0]
	v_pk_mul_f32 v[22:23], v[22:23], v[202:203] op_sel_hi:[1,0]
	v_pk_mul_f32 v[20:21], v[20:21], v[202:203] op_sel_hi:[1,0]
	v_pk_mul_f32 v[18:19], v[18:19], v[202:203] op_sel_hi:[1,0]
	v_pk_mul_f32 v[16:17], v[16:17], v[202:203] op_sel_hi:[1,0]
	v_pk_mul_f32 v[14:15], v[14:15], v[202:203] op_sel_hi:[1,0]
	v_pk_mul_f32 v[12:13], v[12:13], v[202:203] op_sel_hi:[1,0]
	v_pk_mul_f32 v[10:11], v[10:11], v[202:203] op_sel_hi:[1,0]
	v_pk_mul_f32 v[8:9], v[8:9], v[202:203] op_sel_hi:[1,0]
	v_pk_mul_f32 v[6:7], v[6:7], v[202:203] op_sel_hi:[1,0]
	v_pk_mul_f32 v[4:5], v[4:5], v[202:203] op_sel_hi:[1,0]
	v_pk_mul_f32 v[2:3], v[2:3], v[202:203] op_sel_hi:[1,0]

.LBB0_90:
	v_bfe_i32 v66, v218, 0, 1
	v_bfe_i32 v67, v218, 1, 1
	v_bfe_i32 v68, v218, 2, 1
	v_bfe_i32 v69, v218, 3, 1
	v_bfe_i32 v70, v218, 8, 1
	v_bfe_i32 v71, v218, 9, 1
	v_bfe_i32 v72, v218, 10, 1
	v_bfe_i32 v73, v218, 11, 1
	v_bfe_i32 v74, v218, 16, 1
	v_bfe_i32 v75, v218, 17, 1
	v_bfe_i32 v76, v218, 18, 1
	v_bfe_i32 v77, v218, 19, 1
	v_bfe_i32 v78, v218, 24, 1
	v_bfe_i32 v79, v218, 25, 1
	v_bfe_i32 v80, v218, 26, 1
	v_bfe_i32 v81, v218, 27, 1
	ds_read_b128 v[174:177], v217
	ds_read_b128 v[218:221], v217 offset:32
	ds_read_b128 v[222:225], v217 offset:64
	ds_read_b128 v[226:229], v217 offset:96
	ds_read_b128 v[232:235], v217 offset:128
	ds_read_b128 v[236:239], v217 offset:160
	ds_read_b128 v[240:243], v217 offset:192
	ds_read_b128 v[248:251], v217 offset:224
	v_bfi_b32 v66, v66, v230, v231
	v_bfi_b32 v67, v67, v230, v231
	v_bfi_b32 v68, v68, v230, v231
	v_bfi_b32 v69, v69, v230, v231
	v_bfi_b32 v70, v70, v230, v231
	v_bfi_b32 v71, v71, v230, v231
	v_bfi_b32 v72, v72, v230, v231
	v_bfi_b32 v73, v73, v230, v231
	v_bfi_b32 v74, v74, v230, v231
	v_bfi_b32 v75, v75, v230, v231
	v_bfi_b32 v76, v76, v230, v231
	v_bfi_b32 v77, v77, v230, v231
	v_bfi_b32 v78, v78, v230, v231
	v_bfi_b32 v79, v79, v230, v231
	v_bfi_b32 v80, v80, v230, v231
	v_bfi_b32 v81, v81, v230, v231
	s_setprio 1
	s_waitcnt lgkmcnt(7)
	v_mfma_f32_32x32x16_bf16 v[66:81], v[174:177], v[98:101], v[66:81]
	ds_read_b128 v[174:177], v217 offset:8704
	v_bfe_i32 v82, v205, 0, 1
	v_bfe_i32 v83, v205, 1, 1
	v_bfe_i32 v84, v205, 2, 1
	v_bfe_i32 v85, v205, 3, 1
	v_bfe_i32 v86, v205, 8, 1
	s_waitcnt lgkmcnt(7)
	v_mfma_f32_32x32x16_bf16 v[66:81], v[218:221], v[102:105], v[66:81]
	ds_read_b128 v[218:221], v217 offset:8736
	v_bfe_i32 v87, v205, 9, 1
	v_bfe_i32 v88, v205, 10, 1
	v_bfe_i32 v89, v205, 11, 1
	v_bfe_i32 v90, v205, 16, 1
	v_bfe_i32 v91, v205, 17, 1
	s_waitcnt lgkmcnt(7)
	v_mfma_f32_32x32x16_bf16 v[66:81], v[222:225], v[106:109], v[66:81]
	ds_read_b128 v[222:225], v217 offset:8768
	v_bfe_i32 v92, v205, 18, 1
	v_bfe_i32 v93, v205, 19, 1
	v_bfe_i32 v94, v205, 24, 1
	v_bfe_i32 v95, v205, 25, 1
	v_bfe_i32 v96, v205, 26, 1
	s_waitcnt lgkmcnt(7)
	v_mfma_f32_32x32x16_bf16 v[66:81], v[226:229], v[110:113], v[66:81]
	ds_read_b128 v[226:229], v217 offset:8800
	v_bfe_i32 v97, v205, 27, 1
	v_bfi_b32 v82, v82, v230, v231
	v_bfi_b32 v83, v83, v230, v231
	v_bfi_b32 v84, v84, v230, v231
	v_bfi_b32 v85, v85, v230, v231
	s_waitcnt lgkmcnt(7)
	v_mfma_f32_32x32x16_bf16 v[66:81], v[232:235], v[114:117], v[66:81]
	ds_read_b128 v[232:235], v217 offset:8832
	v_bfi_b32 v86, v86, v230, v231
	v_bfi_b32 v87, v87, v230, v231
	v_bfi_b32 v88, v88, v230, v231
	v_bfi_b32 v89, v89, v230, v231
	s_waitcnt lgkmcnt(7)
	v_mfma_f32_32x32x16_bf16 v[66:81], v[236:239], v[118:121], v[66:81]
	ds_read_b128 v[236:239], v217 offset:8864
	v_bfi_b32 v90, v90, v230, v231
	v_bfi_b32 v91, v91, v230, v231
	v_bfi_b32 v92, v92, v230, v231
	v_bfi_b32 v93, v93, v230, v231
	s_waitcnt lgkmcnt(7)
	v_mfma_f32_32x32x16_bf16 v[66:81], v[240:243], v[122:125], v[66:81]
	ds_read_b128 v[240:243], v217 offset:8896
	v_bfi_b32 v94, v94, v230, v231
	v_bfi_b32 v95, v95, v230, v231
	v_bfi_b32 v96, v96, v230, v231
	v_bfi_b32 v97, v97, v230, v231
	s_waitcnt lgkmcnt(7)
	v_mfma_f32_32x32x16_bf16 v[66:81], v[248:251], v[126:129], v[66:81]
	ds_read_b128 v[248:251], v217 offset:8928
	s_waitcnt lgkmcnt(7)
	v_mfma_f32_32x32x16_bf16 v[82:97], v[174:177], v[98:101], v[82:97]
	s_waitcnt lgkmcnt(6)
	v_mfma_f32_32x32x16_bf16 v[82:97], v[218:221], v[102:105], v[82:97]
	s_waitcnt lgkmcnt(5)
	v_mfma_f32_32x32x16_bf16 v[82:97], v[222:225], v[106:109], v[82:97]
	v_max3_f32 v195, v231, v66, v67
	v_max3_f32 v195, v195, v68, v69
	s_waitcnt lgkmcnt(4)
	v_mfma_f32_32x32x16_bf16 v[82:97], v[226:229], v[110:113], v[82:97]
	v_max3_f32 v195, v195, v70, v71
	v_max3_f32 v195, v195, v72, v73
	s_waitcnt lgkmcnt(3)
	v_mfma_f32_32x32x16_bf16 v[82:97], v[232:235], v[114:117], v[82:97]
	v_max3_f32 v195, v195, v74, v75
	v_max3_f32 v195, v195, v76, v77
	s_waitcnt lgkmcnt(2)
	v_mfma_f32_32x32x16_bf16 v[82:97], v[236:239], v[118:121], v[82:97]
	v_max3_f32 v195, v195, v78, v79
	v_max3_f32 v195, v195, v80, v81
	s_waitcnt lgkmcnt(1)
	v_mfma_f32_32x32x16_bf16 v[82:97], v[240:243], v[122:125], v[82:97]
	s_waitcnt lgkmcnt(0)
	v_mfma_f32_32x32x16_bf16 v[82:97], v[248:251], v[126:129], v[82:97]
	s_setprio 0
	s_nop 10
	v_max3_f32 v174, v195, v82, v83
	v_max3_f32 v174, v174, v84, v85
	v_max3_f32 v174, v174, v86, v87
	v_max3_f32 v174, v174, v88, v89
	v_max3_f32 v174, v174, v90, v91
	v_max3_f32 v174, v174, v92, v93
	v_max3_f32 v174, v174, v94, v95
	v_max3_f32 v174, v174, v96, v97
	v_mov_b32_e32 v175, v174
	s_nop 1
	v_permlane32_swap_b32_e32 v174, v175
	v_max_f32_e32 v174, v174, v175
	v_cmp_gt_f32_e32 vcc, v174, v245
	s_cmp_eq_u64 vcc, 0
	s_cbranch_scc1 .Lsmf_2
	v_cndmask_b32_e32 v193, 0, v174, vcc
	v_mov_b32_e32 v175, 0x41000000
	v_cndmask_b32_e32 v245, v245, v175, vcc
	v_sub_f32_e32 v230, v230, v193
	v_max_f32_e32 v175, 0, v193
	v_exp_f32_e64 v204, -v175
	s_nop 0
	v_pk_mul_f32 v[64:65], v[64:65], v[204:205] op_sel_hi:[1,0]
	v_pk_mul_f32 v[62:63], v[62:63], v[204:205] op_sel_hi:[1,0]
	v_pk_mul_f32 v[60:61], v[60:61], v[204:205] op_sel_hi:[1,0]
	v_pk_mul_f32 v[58:59], v[58:59], v[204:205] op_sel_hi:[1,0]
	v_pk_mul_f32 v[56:57], v[56:57], v[204:205] op_sel_hi:[1,0]
	v_pk_mul_f32 v[54:55], v[54:55], v[204:205] op_sel_hi:[1,0]
	v_pk_mul_f32 v[52:53], v[52:53], v[204:205] op_sel_hi:[1,0]
	v_pk_mul_f32 v[50:51], v[50:51], v[204:205] op_sel_hi:[1,0]
	v_pk_mul_f32 v[48:49], v[48:49], v[204:205] op_sel_hi:[1,0]
	v_pk_mul_f32 v[46:47], v[46:47], v[204:205] op_sel_hi:[1,0]
	v_pk_mul_f32 v[44:45], v[44:45], v[204:205] op_sel_hi:[1,0]
	v_pk_mul_f32 v[42:43], v[42:43], v[204:205] op_sel_hi:[1,0]
	v_pk_mul_f32 v[40:41], v[40:41], v[204:205] op_sel_hi:[1,0]
	v_pk_mul_f32 v[38:39], v[38:39], v[204:205] op_sel_hi:[1,0]
	v_pk_mul_f32 v[36:37], v[36:37], v[204:205] op_sel_hi:[1,0]
	v_pk_mul_f32 v[34:35], v[34:35], v[204:205] op_sel_hi:[1,0]
	v_pk_mul_f32 v[32:33], v[32:33], v[204:205] op_sel_hi:[1,0]
	v_pk_mul_f32 v[30:31], v[30:31], v[204:205] op_sel_hi:[1,0]
	v_pk_mul_f32 v[28:29], v[28:29], v[204:205] op_sel_hi:[1,0]
	v_pk_mul_f32 v[26:27], v[26:27], v[204:205] op_sel_hi:[1,0]
	v_pk_mul_f32 v[24:25], v[24:25], v[204:205] op_sel_hi:[1,0]
	v_pk_mul_f32 v[22:23], v[22:23], v[204:205] op_sel_hi:[1,0]
	v_pk_mul_f32 v[20:21], v[20:21], v[204:205] op_sel_hi:[1,0]
	v_pk_mul_f32 v[18:19], v[18:19], v[204:205] op_sel_hi:[1,0]
	v_pk_mul_f32 v[16:17], v[16:17], v[204:205] op_sel_hi:[1,0]
	v_pk_mul_f32 v[14:15], v[14:15], v[204:205] op_sel_hi:[1,0]
	v_pk_mul_f32 v[12:13], v[12:13], v[204:205] op_sel_hi:[1,0]
	v_pk_mul_f32 v[10:11], v[10:11], v[204:205] op_sel_hi:[1,0]
	v_pk_mul_f32 v[8:9], v[8:9], v[204:205] op_sel_hi:[1,0]
	v_pk_mul_f32 v[6:7], v[6:7], v[204:205] op_sel_hi:[1,0]
	v_pk_mul_f32 v[4:5], v[4:5], v[204:205] op_sel_hi:[1,0]
	v_pk_mul_f32 v[2:3], v[2:3], v[204:205] op_sel_hi:[1,0]
